# v8 + write-through (sc1) on the tail weight-conversion stores only
# speedup vs baseline: 1.0020x; 1.0020x over previous
; #define LAS __attribute__((address_space(3)))
; __device__ __forceinline__ unsigned pk2(float lo, float hi) { const f32x2 v = {lo, hi}; return __builtin_bit_cast(unsigned, __builtin_convertvector(v, bf16x2_t)); }
; #define LDS_WAIT() asm volatile("s_waitcnt lgkmcnt(0)" ::: "memory")
; __device__ __forceinline__ void citem_store(const CDesc& d, const CPos& p, int lane, const CRegs& R, LAS float* scr) {
; #pragma unroll
;     for (int i = 0; i < 32; ++i) { const int kk = 2 * i + (lane >> 5); scr[kk * 33 + (lane & 31)] = R.wv[i]; }
;     LDS_WAIT(); asm volatile("" ::: "memory");
;     const int c = lane & 7;
; #pragma unroll
;     for (int j = 0; j < 4; ++j) { const int n = (lane >> 3) + 8 * j; const LAS float* s_ = scr + (8 * c) * 33 + n;
;         u32x4 o; o.x = pk2(s_[0 * 33] * R.g0[0], s_[1 * 33] * R.g0[1]); o.y = pk2(s_[2 * 33] * R.g0[2], s_[3 * 33] * R.g0[3]); o.z = pk2(s_[4 * 33] * R.g1[0], s_[5 * 33] * R.g1[1]); o.w = pk2(s_[6 * 33] * R.g1[2], s_[7 * 33] * R.g1[3]);
;         *(u32x4*)(d.WT + (size_t)(p.drow0 + n) * d.K + p.k0 + 8 * c) = o; }
;     LDS_WAIT(); asm volatile("" ::: "memory");
; }
; __device__ __forceinline__ void conv_batch8(const CDesc& d, int r0, LAS float* scr, int lane) {
;     ...
;     for (int q = 0; q < 8; q += 2) {
;         pb = citem_pos(d, r0 + q + 1); citem_load(d, pb, lane, B);
;         citem_store(d, pa, lane, A, scr);
;         if (q + 2 < 8) { pa = citem_pos(d, r0 + q + 2); citem_load(d, pa, lane, A); }
;         citem_store(d, pb, lane, B, scr);
.LBB0_186:
	s_waitcnt vmcnt(34)
	ds_write2_b32 v31, v64, v65 offset1:66
	s_waitcnt vmcnt(32)
	ds_write2_b32 v31, v66, v67 offset0:132 offset1:198
	s_waitcnt vmcnt(30)
	ds_write2_b32 v96, v68, v69 offset0:8 offset1:74
	s_waitcnt vmcnt(28)
	ds_write2_b32 v96, v70, v71 offset0:140 offset1:206
	s_waitcnt vmcnt(26)
	ds_write2_b32 v97, v72, v73 offset0:16 offset1:82
	s_waitcnt vmcnt(24)
	ds_write2_b32 v97, v74, v75 offset0:148 offset1:214
	s_waitcnt vmcnt(22)
	ds_write2_b32 v98, v76, v77 offset0:24 offset1:90
	s_waitcnt vmcnt(20)
	ds_write2_b32 v98, v78, v79 offset0:156 offset1:222
	s_waitcnt vmcnt(18)
	ds_write2_b32 v99, v80, v81 offset0:32 offset1:98
	s_waitcnt vmcnt(16)
	ds_write2_b32 v99, v82, v83 offset0:164 offset1:230
	s_waitcnt vmcnt(14)
	ds_write2_b32 v100, v84, v85 offset0:40 offset1:106
	s_waitcnt vmcnt(12)
	ds_write2_b32 v100, v86, v87 offset0:172 offset1:238
	s_waitcnt vmcnt(10)
	ds_write2_b32 v101, v88, v89 offset0:48 offset1:114
	s_waitcnt vmcnt(8)
	ds_write2_b32 v101, v90, v91 offset0:180 offset1:246
	s_waitcnt vmcnt(6)
	ds_write2_b32 v102, v92, v93 offset0:56 offset1:122
	s_waitcnt vmcnt(4)
	ds_write2_b32 v102, v94, v95 offset0:188 offset1:254
	s_waitcnt lgkmcnt(0)
	ds_read2_b32 v[68:69], v30 offset1:8
	ds_read2_b32 v[70:71], v30 offset0:33 offset1:41
	ds_read2_b32 v[72:73], v30 offset0:66 offset1:74
	ds_read2_b32 v[74:75], v30 offset0:99 offset1:107
	ds_read2_b32 v[76:77], v30 offset0:132 offset1:140
	ds_read2_b32 v[78:79], v30 offset0:165 offset1:173
	ds_read2_b32 v[80:81], v30 offset0:198 offset1:206
	ds_read2_b32 v[82:83], v30 offset0:231 offset1:239
	s_waitcnt lgkmcnt(7)
	v_mov_b32_e32 v64, v68
	s_waitcnt lgkmcnt(6)
	v_mov_b32_e32 v65, v70
	s_waitcnt lgkmcnt(5)
	v_mov_b32_e32 v66, v72
	s_waitcnt lgkmcnt(4)
	v_mov_b32_e32 v67, v74
	v_pk_mul_f32 v[64:65], v[14:15], v[64:65]
	v_pk_mul_f32 v[66:67], v[16:17], v[66:67]
	v_cvt_pk_bf16_f32 v64, v64, v65
	v_cvt_pk_bf16_f32 v65, v66, v67
	s_waitcnt lgkmcnt(3)
	v_mov_b32_e32 v66, v76
	s_waitcnt lgkmcnt(2)
	v_mov_b32_e32 v67, v78
	s_waitcnt lgkmcnt(1)
	v_mov_b32_e32 v84, v80
	s_waitcnt lgkmcnt(0)
	v_mov_b32_e32 v85, v82
	v_add_u32_e32 v25, s88, v26
	v_pk_mul_f32 v[66:67], v[18:19], v[66:67]
	v_pk_mul_f32 v[84:85], v[20:21], v[84:85]
	v_ashrrev_i32_e32 v68, 31, v25
	v_cvt_pk_bf16_f32 v66, v66, v67
	v_cvt_pk_bf16_f32 v67, v84, v85
	v_mul_lo_u32 v68, s46, v68
	v_mul_lo_u32 v70, s47, v25
	v_mad_u64_u32 v[84:85], s[40:41], s46, v25, 0
	v_add3_u32 v85, v85, v68, v70
	v_lshl_add_u64 v[84:85], v[84:85], 1, s[44:45]
	s_lshl_b64 s[40:41], s[54:55], 1
	v_lshl_add_u64 v[84:85], v[84:85], 0, s[40:41]
	v_mov_b32_e32 v25, v5
	v_lshl_add_u64 v[84:85], v[84:85], 0, v[24:25]
	v_mov_b32_e32 v70, v69
	v_mov_b32_e32 v74, v73
	global_store_dwordx4 v[84:85], v[64:67], off sc1
	v_mov_b32_e32 v78, v77
	v_mov_b32_e32 v82, v81
	v_pk_mul_f32 v[64:65], v[14:15], v[70:71]
	v_pk_mul_f32 v[66:67], v[16:17], v[74:75]
	v_cvt_pk_bf16_f32 v64, v64, v65
	v_cvt_pk_bf16_f32 v65, v66, v67
	v_pk_mul_f32 v[66:67], v[18:19], v[78:79]
	v_pk_mul_f32 v[68:69], v[20:21], v[82:83]
	v_cvt_pk_bf16_f32 v66, v66, v67
	v_cvt_pk_bf16_f32 v67, v68, v69
	v_add_u32_e32 v68, s88, v27
	v_ashrrev_i32_e32 v69, 31, v68
	v_mul_lo_u32 v70, s46, v69
	v_mul_lo_u32 v71, s47, v68
	v_mad_u64_u32 v[68:69], s[54:55], s46, v68, 0
	v_add3_u32 v69, v69, v70, v71
	v_lshl_add_u64 v[68:69], v[68:69], 1, s[44:45]
	v_lshl_add_u64 v[68:69], v[68:69], 0, s[40:41]
	v_lshl_add_u64 v[68:69], v[68:69], 0, v[24:25]
	ds_read2_b32 v[70:71], v30 offset0:16 offset1:24
	ds_read2_b32 v[72:73], v30 offset0:49 offset1:57
	global_store_dwordx4 v[68:69], v[64:67], off sc1
	ds_read2_b32 v[68:69], v30 offset0:82 offset1:90
	ds_read2_b32 v[74:75], v30 offset0:115 offset1:123
	ds_read2_b32 v[76:77], v30 offset0:148 offset1:156
	ds_read2_b32 v[78:79], v30 offset0:181 offset1:189
	ds_read2_b32 v[80:81], v30 offset0:214 offset1:222
	ds_read2_b32 v[82:83], v30 offset0:247 offset1:255
	s_waitcnt lgkmcnt(7)
	v_mov_b32_e32 v64, v70
	s_waitcnt lgkmcnt(6)
	v_mov_b32_e32 v65, v72
	s_waitcnt lgkmcnt(5)
	v_mov_b32_e32 v66, v68
	s_waitcnt lgkmcnt(4)
	v_mov_b32_e32 v67, v74
	v_pk_mul_f32 v[64:65], v[14:15], v[64:65]
	v_pk_mul_f32 v[66:67], v[16:17], v[66:67]
	v_cvt_pk_bf16_f32 v64, v64, v65
	v_cvt_pk_bf16_f32 v65, v66, v67
	s_waitcnt lgkmcnt(3)
	v_mov_b32_e32 v66, v76
	s_waitcnt lgkmcnt(2)
	v_mov_b32_e32 v67, v78
	s_waitcnt lgkmcnt(1)
	v_mov_b32_e32 v84, v80
	s_waitcnt lgkmcnt(0)
	v_mov_b32_e32 v85, v82
	v_add_u32_e32 v68, s88, v28
	v_pk_mul_f32 v[66:67], v[18:19], v[66:67]
	v_pk_mul_f32 v[84:85], v[20:21], v[84:85]
	v_ashrrev_i32_e32 v70, 31, v68
	v_cvt_pk_bf16_f32 v66, v66, v67
	v_cvt_pk_bf16_f32 v67, v84, v85
	v_mul_lo_u32 v70, s46, v70
	v_mul_lo_u32 v72, s47, v68
	v_mad_u64_u32 v[84:85], s[54:55], s46, v68, 0
	v_add3_u32 v85, v85, v70, v72
	v_mov_b32_e32 v72, v71
	v_mov_b32_e32 v74, v69
	v_pk_mul_f32 v[14:15], v[14:15], v[72:73]
	v_pk_mul_f32 v[16:17], v[16:17], v[74:75]
	v_mov_b32_e32 v78, v77
	v_mov_b32_e32 v82, v81
	v_cvt_pk_bf16_f32 v14, v14, v15
	v_cvt_pk_bf16_f32 v15, v16, v17
	v_pk_mul_f32 v[16:17], v[18:19], v[78:79]
	v_pk_mul_f32 v[18:19], v[20:21], v[82:83]
	v_cvt_pk_bf16_f32 v16, v16, v17
	v_cvt_pk_bf16_f32 v17, v18, v19
	v_add_u32_e32 v18, s88, v29
	v_ashrrev_i32_e32 v19, 31, v18
	v_mul_lo_u32 v20, s46, v19
	v_mul_lo_u32 v21, s47, v18
	v_mad_u64_u32 v[18:19], s[54:55], s46, v18, 0
	v_add3_u32 v19, v19, v20, v21
	v_lshl_add_u64 v[84:85], v[84:85], 1, s[44:45]
	v_lshl_add_u64 v[18:19], v[18:19], 1, s[44:45]
	v_lshl_add_u64 v[84:85], v[84:85], 0, s[40:41]
	v_lshl_add_u64 v[18:19], v[18:19], 0, s[40:41]
	v_lshl_add_u64 v[84:85], v[84:85], 0, v[24:25]
	v_lshl_add_u64 v[18:19], v[18:19], 0, v[24:25]
	global_store_dwordx4 v[84:85], v[64:67], off sc1
	global_store_dwordx4 v[18:19], v[14:17], off sc1
	s_waitcnt lgkmcnt(0)
	s_add_i32 s80, s80, 2
	s_addk_i32 s82, 0x80
	s_addk_i32 s84, 0x100
	s_add_i32 s87, s87, 64
	s_and_b64 vcc, exec, s[56:57]
	s_cbranch_vccnz .LBB0_145

; #define LAS __attribute__((address_space(3)))
; __device__ __forceinline__ unsigned pk2(float lo, float hi) { const f32x2 v = {lo, hi}; return __builtin_bit_cast(unsigned, __builtin_convertvector(v, bf16x2_t)); }
; #define LDS_WAIT() asm volatile("s_waitcnt lgkmcnt(0)" ::: "memory")
; __device__ __forceinline__ void citem_store(const CDesc& d, const CPos& p, int lane, const CRegs& R, LAS float* scr) {
; #pragma unroll
;     for (int i = 0; i < 32; ++i) { const int kk = 2 * i + (lane >> 5); scr[kk * 33 + (lane & 31)] = R.wv[i]; }
;     LDS_WAIT(); asm volatile("" ::: "memory");
;     const int c = lane & 7;
; #pragma unroll
;     for (int j = 0; j < 4; ++j) { const int n = (lane >> 3) + 8 * j; const LAS float* s_ = scr + (8 * c) * 33 + n;
;         u32x4 o; o.x = pk2(s_[0 * 33] * R.g0[0], s_[1 * 33] * R.g0[1]); o.y = pk2(s_[2 * 33] * R.g0[2], s_[3 * 33] * R.g0[3]); o.z = pk2(s_[4 * 33] * R.g1[0], s_[5 * 33] * R.g1[1]); o.w = pk2(s_[6 * 33] * R.g1[2], s_[7 * 33] * R.g1[3]);
;         *(u32x4*)(d.WT + (size_t)(p.drow0 + n) * d.K + p.k0 + 8 * c) = o; }
;     LDS_WAIT(); asm volatile("" ::: "memory");
; }
.LBB0_203:
	v_add_u32_e32 v96, 0x400, v31
	v_add_u32_e32 v97, 0x800, v31
	v_add_u32_e32 v98, 0xc00, v31
	v_add_u32_e32 v99, 0x1000, v31
	v_add_u32_e32 v100, 0x1400, v31
	v_add_u32_e32 v101, 0x1800, v31
	v_add_u32_e32 v102, 0x1c00, v31
	s_waitcnt vmcnt(62)
	ds_write2_b32 v31, v32, v33 offset1:66
	s_waitcnt vmcnt(60)
	ds_write2_b32 v31, v34, v35 offset0:132 offset1:198
	s_waitcnt vmcnt(58)
	ds_write2_b32 v96, v36, v37 offset0:8 offset1:74
	s_waitcnt vmcnt(56)
	ds_write2_b32 v96, v38, v39 offset0:140 offset1:206
	s_waitcnt vmcnt(54)
	ds_write2_b32 v97, v40, v41 offset0:16 offset1:82
	s_waitcnt vmcnt(52)
	ds_write2_b32 v97, v42, v43 offset0:148 offset1:214
	s_waitcnt vmcnt(50)
	ds_write2_b32 v98, v44, v45 offset0:24 offset1:90
	s_waitcnt vmcnt(48)
	ds_write2_b32 v98, v46, v47 offset0:156 offset1:222
	s_waitcnt vmcnt(46)
	ds_write2_b32 v99, v48, v49 offset0:32 offset1:98
	s_waitcnt vmcnt(44)
	ds_write2_b32 v99, v50, v51 offset0:164 offset1:230
	s_waitcnt vmcnt(42)
	ds_write2_b32 v100, v52, v53 offset0:40 offset1:106
	s_waitcnt vmcnt(40)
	ds_write2_b32 v100, v54, v55 offset0:172 offset1:238
	s_waitcnt vmcnt(38)
	ds_write2_b32 v101, v56, v57 offset0:48 offset1:114
	s_waitcnt vmcnt(36)
	ds_write2_b32 v101, v58, v59 offset0:180 offset1:246
	s_waitcnt vmcnt(34)
	ds_write2_b32 v102, v60, v61 offset0:56 offset1:122
	s_waitcnt vmcnt(32)
	ds_write2_b32 v102, v62, v63 offset0:188 offset1:254
	s_waitcnt lgkmcnt(0)
	ds_read2_b32 v[108:109], v30 offset1:8
	ds_read2_b32 v[110:111], v30 offset0:33 offset1:41
	ds_read2_b32 v[112:113], v30 offset0:66 offset1:74
	ds_read2_b32 v[114:115], v30 offset0:99 offset1:107
	ds_read2_b32 v[116:117], v30 offset0:132 offset1:140
	ds_read2_b32 v[118:119], v30 offset0:165 offset1:173
	s_waitcnt lgkmcnt(5)
	v_mov_b32_e32 v24, v108
	s_waitcnt lgkmcnt(4)
	v_mov_b32_e32 v25, v110
	v_pk_mul_f32 v[24:25], v[6:7], v[24:25]
	ds_read2_b32 v[120:121], v30 offset0:198 offset1:206
	ds_read2_b32 v[122:123], v30 offset0:231 offset1:239
	v_cvt_pk_bf16_f32 v104, v24, v25
	s_waitcnt lgkmcnt(5)
	v_mov_b32_e32 v24, v112
	s_waitcnt lgkmcnt(4)
	v_mov_b32_e32 v25, v114
	v_pk_mul_f32 v[24:25], v[8:9], v[24:25]
	s_ashr_i32 s53, s52, 31
	v_cvt_pk_bf16_f32 v105, v24, v25
	s_waitcnt lgkmcnt(3)
	v_mov_b32_e32 v24, v116
	s_waitcnt lgkmcnt(2)
	v_mov_b32_e32 v25, v118
	v_pk_mul_f32 v[24:25], v[10:11], v[24:25]
	v_mov_b32_e32 v110, v109
	v_cvt_pk_bf16_f32 v106, v24, v25
	s_waitcnt lgkmcnt(1)
	v_mov_b32_e32 v24, v120
	s_waitcnt lgkmcnt(0)
	v_mov_b32_e32 v25, v122
	v_pk_mul_f32 v[24:25], v[12:13], v[24:25]
	v_mov_b32_e32 v114, v113
	v_cvt_pk_bf16_f32 v107, v24, v25
	v_add_u32_e32 v24, s78, v26
	v_ashrrev_i32_e32 v25, 31, v24
	v_mul_lo_u32 v103, s46, v25
	v_mul_lo_u32 v108, s47, v24
	v_mad_u64_u32 v[24:25], s[56:57], s46, v24, 0
	v_add3_u32 v25, v25, v103, v108
	v_lshl_add_u64 v[24:25], v[24:25], 1, s[44:45]
	s_lshl_b64 s[56:57], s[52:53], 1
	v_lshl_add_u64 v[124:125], v[24:25], 0, s[56:57]
	v_lshlrev_b32_e32 v24, 1, v2
	v_mov_b32_e32 v25, v5
	v_lshl_add_u64 v[124:125], v[124:125], 0, v[24:25]
	global_store_dwordx4 v[124:125], v[104:107], off sc1
	v_mov_b32_e32 v118, v117
	v_mov_b32_e32 v122, v121
	v_pk_mul_f32 v[104:105], v[6:7], v[110:111]
	v_pk_mul_f32 v[106:107], v[8:9], v[114:115]
	v_cvt_pk_bf16_f32 v104, v104, v105
	v_cvt_pk_bf16_f32 v105, v106, v107
	v_pk_mul_f32 v[106:107], v[10:11], v[118:119]
	v_pk_mul_f32 v[108:109], v[12:13], v[122:123]
	v_add_u32_e32 v103, s78, v27
	v_cvt_pk_bf16_f32 v106, v106, v107
	v_cvt_pk_bf16_f32 v107, v108, v109
	v_ashrrev_i32_e32 v108, 31, v103
	v_mul_lo_u32 v110, s46, v108
	v_mul_lo_u32 v111, s47, v103
	v_mad_u64_u32 v[108:109], s[58:59], s46, v103, 0
	v_add3_u32 v109, v109, v110, v111
	v_lshl_add_u64 v[108:109], v[108:109], 1, s[44:45]
	v_lshl_add_u64 v[108:109], v[108:109], 0, s[56:57]
	v_lshl_add_u64 v[108:109], v[108:109], 0, v[24:25]
	ds_read2_b32 v[110:111], v30 offset0:16 offset1:24
	ds_read2_b32 v[112:113], v30 offset0:49 offset1:57
	global_store_dwordx4 v[108:109], v[104:107], off sc1
	ds_read2_b32 v[108:109], v30 offset0:82 offset1:90
	ds_read2_b32 v[114:115], v30 offset0:115 offset1:123
	ds_read2_b32 v[116:117], v30 offset0:148 offset1:156
	ds_read2_b32 v[118:119], v30 offset0:181 offset1:189
	ds_read2_b32 v[120:121], v30 offset0:214 offset1:222
	ds_read2_b32 v[122:123], v30 offset0:247 offset1:255
	s_waitcnt lgkmcnt(7)
	v_mov_b32_e32 v104, v110
	s_waitcnt lgkmcnt(6)
	v_mov_b32_e32 v105, v112
	s_waitcnt lgkmcnt(5)
	v_mov_b32_e32 v106, v108
	s_waitcnt lgkmcnt(4)
	v_mov_b32_e32 v107, v114
	v_pk_mul_f32 v[104:105], v[6:7], v[104:105]
	v_pk_mul_f32 v[106:107], v[8:9], v[106:107]
	v_cvt_pk_bf16_f32 v104, v104, v105
	v_cvt_pk_bf16_f32 v105, v106, v107
	s_waitcnt lgkmcnt(3)
	v_mov_b32_e32 v106, v116
	s_waitcnt lgkmcnt(2)
	v_mov_b32_e32 v107, v118
	s_waitcnt lgkmcnt(1)
	v_mov_b32_e32 v124, v120
	s_waitcnt lgkmcnt(0)
	v_mov_b32_e32 v125, v122
	v_add_u32_e32 v103, s78, v28
	v_pk_mul_f32 v[106:107], v[10:11], v[106:107]
	v_pk_mul_f32 v[124:125], v[12:13], v[124:125]
	v_ashrrev_i32_e32 v108, 31, v103
	v_cvt_pk_bf16_f32 v106, v106, v107
	v_cvt_pk_bf16_f32 v107, v124, v125
	v_mul_lo_u32 v108, s46, v108
	v_mul_lo_u32 v110, s47, v103
	v_mad_u64_u32 v[124:125], s[58:59], s46, v103, 0
	v_add3_u32 v125, v125, v108, v110
	v_lshl_add_u64 v[124:125], v[124:125], 1, s[44:45]
	v_lshl_add_u64 v[124:125], v[124:125], 0, s[56:57]
	v_lshl_add_u64 v[124:125], v[124:125], 0, v[24:25]
	v_mov_b32_e32 v112, v111
	v_mov_b32_e32 v114, v109
	global_store_dwordx4 v[124:125], v[104:107], off sc1
	v_mov_b32_e32 v118, v117
	v_mov_b32_e32 v122, v121
	v_pk_mul_f32 v[104:105], v[6:7], v[112:113]
	v_pk_mul_f32 v[106:107], v[8:9], v[114:115]
	v_cvt_pk_bf16_f32 v104, v104, v105
	v_cvt_pk_bf16_f32 v105, v106, v107
	v_pk_mul_f32 v[106:107], v[10:11], v[118:119]
	v_pk_mul_f32 v[108:109], v[12:13], v[122:123]
	v_add_u32_e32 v103, s78, v29
	v_cvt_pk_bf16_f32 v106, v106, v107
	v_cvt_pk_bf16_f32 v107, v108, v109
	v_ashrrev_i32_e32 v108, 31, v103
	v_mul_lo_u32 v110, s46, v108
	v_mul_lo_u32 v111, s47, v103
	v_mad_u64_u32 v[108:109], s[58:59], s46, v103, 0
	v_add3_u32 v109, v109, v110, v111
	v_lshl_add_u64 v[108:109], v[108:109], 1, s[44:45]
	v_lshl_add_u64 v[108:109], v[108:109], 0, s[56:57]
	v_lshl_add_u64 v[108:109], v[108:109], 0, v[24:25]
	global_store_dwordx4 v[108:109], v[104:107], off sc1
	s_waitcnt lgkmcnt(0)
	s_cmp_gt_u32 s80, 5
	s_cselect_b64 s[56:57], -1, 0
	s_and_b64 vcc, exec, s[56:57]
	s_cbranch_vccnz .LBB0_186
; __device__ __forceinline__ CPos citem_pos(const CDesc& d, int r) {
;     const int nblk = d.N / 32, kb = r / nblk, nb = r - kb * nblk, n0 = 32 * nb;
;     int drow0 = n0;
;     if (d.mode == 1) { const int hn = d.N / 2; drow0 = (n0 < hn) ? ((n0 >> 7) * 256 + (n0 & 127)) : (((n0 - hn) >> 7) * 256 + 128 + ((n0 - hn) & 127)); }
;     else if (d.mode == 2) { const int t = n0 >> 8, w = n0 & 255; drow0 = t * 256 + ((w >> 5) & 1) * 128 + (w >> 6) * 32; }
;     return CPos{64 * kb, n0, drow0};
	s_add_i32 s52, s60, 2
	s_sub_i32 s58, -2, s60
	s_ashr_i32 s53, s52, 31
	s_max_i32 s52, s52, s58
	s_mul_hi_u32 s58, s52, s77
	s_mul_i32 s59, s58, s76
	s_sub_i32 s52, s52, s59
	s_add_i32 s59, s58, 1
	s_sub_i32 s60, s52, s76
	s_cmp_ge_u32 s52, s76
	s_cselect_b32 s58, s59, s58
	s_cselect_b32 s52, s60, s52
	s_add_i32 s59, s58, 1
	s_cmp_ge_u32 s52, s76
	s_cselect_b32 s52, s59, s58
	s_xor_b32 s52, s52, s53
	s_sub_i32 s59, s52, s53
	s_mul_i32 s52, s86, s59
	s_add_i32 s58, s87, s52
	s_mov_b64 s[62:63], -1
	s_mov_b64 s[52:53], 0
	s_cmp_lt_i32 s75, 2
	s_mov_b64 s[60:61], 0
	s_cbranch_scc1 .LBB0_210
	s_cmp_eq_u32 s75, 2
	s_mov_b64 s[60:61], -1
	s_cbranch_scc0 .LBB0_207
	s_mul_i32 s61, s83, s59
	s_add_i32 s61, s84, s61
	s_and_b32 s60, s58, 0xffffff00
	s_and_b32 s61, s61, 0x80
	s_or_b32 s60, s60, s61
	s_lshr_b32 s61, s58, 1
	s_and_b32 s61, s61, 0x60
	s_or_b32 s78, s60, s61
	s_mov_b64 s[60:61], 0
